# v23 + unit-loop headers: the divide by the row-group size (always 4) replaced by shift/and in all four GEMMs
# speedup vs baseline: 1.0152x; 1.0037x over previous
;     __host__ __device__ bool next(int i, Unit& u) const {
;         const long L = (long)i * G + c; if (L >= nwg) return false;
;         int wgid = (int)L; { const int q = nwg / NXCD, r = nwg % NXCD, xcd = wgid % NXCD, off = wgid / NXCD; wgid = (xcd < r ? xcd * (q + 1) : r * (q + 1) + (xcd - r) * q) + off; }
;         const int nig = wgm * nN, gid = wgid / nig, fm = gid * wgm, gsz = (nM - fm) < wgm ? (nM - fm) : wgm;
;         u.pm = fm + ((wgid % nig) % gsz); u.pn = (wgid % nig) / gsz; u.idx = i; if (rev) u.pm = nM - 1 - u.pm; return true;
.LBB0_155:
	s_add_i32 s71, s71, 1
	s_mul_i32 s21, s71, s90
	s_mul_hi_u32 s22, s71, s30
	s_add_i32 s22, s22, s21
	s_mul_i32 s21, s71, s30
	s_add_u32 s80, s21, s60
	s_addc_u32 s81, s22, s61
	v_mov_b64_e32 v[0:1], 0x600
	v_cmp_lt_i64_e64 s[38:39], s[80:81], v[0:1]
	v_mov_b64_e32 v[0:1], 0x5ff
	v_cmp_gt_i64_e32 vcc, s[80:81], v[0:1]
	s_cbranch_vccnz .LBB0_157
	s_ashr_i32 s21, s80, 31
	s_lshr_b32 s21, s21, 29
	s_add_i32 s21, s80, s21
	s_ashr_i32 s22, s21, 3
	s_and_b32 s21, s21, -8
	s_sub_i32 s21, s80, s21
	s_cmp_lt_i32 s21, 0
	s_cselect_b32 s23, s3, 0xc0
	s_mul_i32 s21, s23, s21
	s_add_i32 s21, s21, s22
	s_ashr_i32 s22, s21, 31
	s_lshr_b32 s22, s22, 27
	s_add_i32 s22, s21, s22
	s_ashr_i32 s23, s22, 5
	s_lshl_b32 s23, s23, 2
	s_andn2_b32 s22, s22, 31
	s_sub_i32 s21, s21, s22
	s_mov_b32 s44, s71
	s_lshr_b32 s76, s21, 2
	s_and_b32 s21, s21, 3
	s_add_i32 s78, s21, s23

;     __host__ __device__ bool next(int i, Unit& u) const {
;         const long L = (long)i * G + c; if (L >= nwg) return false;
;         int wgid = (int)L; { const int q = nwg / NXCD, r = nwg % NXCD, xcd = wgid % NXCD, off = wgid / NXCD; wgid = (xcd < r ? xcd * (q + 1) : r * (q + 1) + (xcd - r) * q) + off; }
;         const int nig = wgm * nN, gid = wgid / nig, fm = gid * wgm, gsz = (nM - fm) < wgm ? (nM - fm) : wgm;
;         u.pm = fm + ((wgid % nig) % gsz); u.pn = (wgid % nig) / gsz; u.idx = i; if (rev) u.pm = nM - 1 - u.pm; return true;
.LBB0_437:
	s_add_i32 s0, s0, 1
	s_mul_i32 s36, s0, s44
	s_mul_hi_u32 s37, s0, s30
	s_add_i32 s37, s37, s36
	s_mul_i32 s36, s0, s30
	s_add_u32 s72, s36, s60
	s_addc_u32 s73, s37, s61
	v_mov_b64_e32 v[0:1], 0x480
	v_cmp_lt_i64_e64 s[36:37], s[72:73], v[0:1]
	v_mov_b64_e32 v[0:1], 0x47f
	v_cmp_gt_i64_e32 vcc, s[72:73], v[0:1]
	s_cbranch_vccnz .LBB0_439
	s_ashr_i32 s65, s72, 31
	s_lshr_b32 s65, s65, 29
	s_add_i32 s65, s72, s65
	s_ashr_i32 s66, s65, 3
	s_and_b32 s65, s65, -8
	s_sub_i32 s65, s72, s65
	s_cmp_lt_i32 s65, 0
	s_movk_i32 s8, 0x91
	s_cselect_b32 s67, s8, 0x90
	s_mul_i32 s65, s67, s65
	s_add_i32 s65, s65, s66
	s_mul_hi_i32 s66, s65, 0x38e38e39
	s_lshr_b32 s67, s66, 31
	s_ashr_i32 s66, s66, 5
	s_add_i32 s66, s66, s67
	s_lshl_b32 s67, s66, 2
	s_mulk_i32 s66, 0x90
	s_sub_i32 s65, s65, s66
	s_lshr_b32 s66, s65, 2
	s_and_b32 s65, s65, 3
	s_add_i32 s8, s65, s67
	s_mov_b32 s65, s0

;     __host__ __device__ bool next(int i, Unit& u) const {
;         const long L = (long)i * G + c; if (L >= nwg) return false;
;         int wgid = (int)L; { const int q = nwg / NXCD, r = nwg % NXCD, xcd = wgid % NXCD, off = wgid / NXCD; wgid = (xcd < r ? xcd * (q + 1) : r * (q + 1) + (xcd - r) * q) + off; }
;         const int nig = wgm * nN, gid = wgid / nig, fm = gid * wgm, gsz = (nM - fm) < wgm ? (nM - fm) : wgm;
;         u.pm = fm + ((wgid % nig) % gsz); u.pn = (wgid % nig) / gsz; u.idx = i; if (rev) u.pm = nM - 1 - u.pm; return true;
.LBB0_501:
	s_add_i32 s21, s21, 1
	s_mul_i32 s26, s21, s67
	s_mul_hi_u32 s27, s21, s30
	s_add_i32 s27, s27, s26
	s_mul_i32 s26, s21, s30
	s_add_u32 s38, s26, s60
	s_addc_u32 s39, s27, s20
	v_cmp_gt_i64_e32 vcc, s[38:39], v[186:187]
	v_cmp_lt_i64_e64 s[40:41], s[38:39], v[188:189]
	s_cbranch_vccnz .LBB0_503
	s_ashr_i32 s22, s38, 31
	s_lshr_b32 s22, s22, 29
	s_add_i32 s22, s38, s22
	s_ashr_i32 s23, s22, 3
	s_and_b32 s22, s22, -8
	s_sub_i32 s22, s38, s22
	s_cmp_lt_i32 s22, 0
	s_movk_i32 s24, 0x61
	s_cselect_b32 s24, s24, 0x60
	s_mul_i32 s22, s24, s22
	s_add_i32 s22, s22, s23
	s_ashr_i32 s23, s22, 31
	s_lshr_b32 s23, s23, 28
	s_add_i32 s23, s22, s23
	s_ashr_i32 s24, s23, 4
	s_lshl_b32 s24, s24, 2
	s_and_b32 s23, s23, -16
	s_sub_i32 s23, s22, s23
	s_lshr_b32 s22, s23, 2
	s_and_b32 s23, s23, 3
	s_add_i32 s23, s23, s24
	s_sub_i32 s24, 0xbf, s23
	s_and_b64 s[26:27], s[14:15], exec
	s_cselect_b32 s24, s24, s23
	s_mov_b32 s23, s21

;     __host__ __device__ bool next(int i, Unit& u) const {
;         const long L = (long)i * G + c; if (L >= nwg) return false;
;         int wgid = (int)L; { const int q = nwg / NXCD, r = nwg % NXCD, xcd = wgid % NXCD, off = wgid / NXCD; wgid = (xcd < r ? xcd * (q + 1) : r * (q + 1) + (xcd - r) * q) + off; }
;         const int nig = wgm * nN, gid = wgid / nig, fm = gid * wgm, gsz = (nM - fm) < wgm ? (nM - fm) : wgm;
;         u.pm = fm + ((wgid % nig) % gsz); u.pn = (wgid % nig) / gsz; u.idx = i; if (rev) u.pm = nM - 1 - u.pm; return true;
.LBB0_777:
	s_add_i32 s74, s74, 1
	s_mul_i32 s36, s74, s0
	s_mul_hi_u32 s37, s74, s30
	s_add_i32 s37, s37, s36
	s_mul_i32 s36, s74, s30
	s_add_u32 s52, s36, s60
	s_addc_u32 s53, s37, s23
	v_cmp_gt_i64_e32 vcc, s[52:53], v[190:191]
	v_cmp_lt_i64_e64 s[36:37], s[52:53], v[192:193]
	s_cbranch_vccnz .LBB0_779
	s_ashr_i32 s42, s52, 31
	s_lshr_b32 s42, s42, 29
	s_add_i32 s42, s52, s42
	s_ashr_i32 s43, s42, 3
	s_and_b32 s42, s42, -8
	s_sub_i32 s42, s52, s42
	s_cmp_lt_i32 s42, 0
	s_movk_i32 s44, 0x211
	s_cselect_b32 s44, s44, 0x210
	s_mul_i32 s42, s44, s42
	s_add_i32 s42, s42, s43
	s_mul_hi_i32 s43, s42, 0x2e8ba2e9
	s_lshr_b32 s44, s43, 31
	s_ashr_i32 s43, s43, 4
	s_add_i32 s43, s43, s44
	s_lshl_b32 s44, s43, 2
	s_mulk_i32 s43, 0x58
	s_sub_i32 s43, s42, s43
	s_mov_b32 s75, s74
	s_lshr_b32 s42, s43, 2
	s_and_b32 s43, s43, 3
	s_add_i32 s44, s43, s44
